# v18 + mixer phase: blocks 0..127 run their extra convpool_sample item first instead of last (no serialized tail)
# baseline (speedup 1.0000x reference)
; DEVI void run_phase(const Params& p, int ph, char* smem) {
;     ...
;     case 1: {
;       const int N1 = 1024, N2 = 512, N3 = 256, N4 = 256, N5 = 1024 + 128, N6 = 384 + 17;
;       const int tot = N1 + N2 + N3 + N4 + N5 + N6;
;       for (int it = blockIdx.x; it < tot; it += G) {
;         int i = it;
;         if (i < N1) {
;           const int b = i >> 7, c = (i >> 2) & 31, h = i & 3;
;           const size_t o = ((size_t)(b * 32 + c) * 4 + h);
;           hgrn_mfma_item<false>(p, l, b * 2048 + c * 64, h, nullptr, (float*)(p.ws + WS_HU) + o * 4096, (float*)(p.ws + WS_HD) + o * 64, smem);
;         } else if ((i -= N1) < N2) {
;           const int sb = i >> 2, h = i & 3;
;           const size_t o = (((size_t)l * 128 + sb) * 4 + h) * 4096;
;           hgrn_item<true, false>(p, l, T_P + sb * 4, 4, h, p.state_hgrn + o, p.out + O_HGRN_S + o, nullptr, smem);
;         } else if ((i -= N2) < N3) {
;           const int b = i >> 5, qb = (i >> 1) & 15, kv = i & 1;
;           const int R0 = b * 2048 + qb * 128;
;           const u16* Kb = proj + (ptrdiff_t)(R0 - 128) * DIN + C_AK + kv * 64;
;           const u16* Vb = proj + (ptrdiff_t)(R0 - 128) * DIN + C_AV + kv * 64;
;           const float s0 = exp2f(-2.f * (float)(kv * 2 + 1)), s1 = exp2f(-2.f * (float)(kv * 2 + 2));
;           attn256_item(Kb, DIN, Vb, qb == 0 ? 128 : 0, proj + (size_t)R0 * DIN + kv * 128, DIN, mix + (size_t)R0 * 1024 + kv * 128, 1024, 1,
;                        s0, s1, p.attn_sink[l * 4 + kv * 2], p.attn_sink[l * 4 + kv * 2 + 1], smem);
;         } else if ((i -= N3) < N4) {
;           attn_small_item<1>(p, l, i >> 1, i & 1, smem);
;         } else if ((i -= N4) < N5) {
;           if (i < 1024) convpool_fast(p, l, i * 16); else convpool_sample(p, l, i - 1024);
;         } else {
;           i -= N5;
;           if (i < 384) kvstate_item(p, l, i); else prompt_state_item(p, l, i - 384);
;         }
;       }
.LBB0_918:
	s_andn2_b64 vcc, exec, s[2:3]
	s_cbranch_vccnz .LBB0_1888
	v_readlane_b32 s2, v251, 38
	v_readlane_b32 s3, v251, 39
	s_andn2_b64 vcc, exec, s[2:3]
	s_cbranch_vccnz .LBB0_1888
	v_readlane_b32 s4, v254, 62
	s_and_b32 s5, 0xffff, s4
	s_lshl_b32 s0, s5, 3
	v_writelane_b32 v255, s0, 0
	s_lshl_b32 s0, s5, 10
	v_writelane_b32 v255, s0, 1
	s_lshl_b32 s3, s4, 2
	s_lshl_b32 s6, s5, 14
	s_lshl_b32 s0, s5, 18
	v_writelane_b32 v255, s3, 2
	v_readlane_b32 s3, v251, 42
	v_writelane_b32 v255, s6, 3
	s_add_u32 s6, s3, s6
	v_readlane_b32 s3, v251, 43
	s_addc_u32 s7, s3, 0
	v_writelane_b32 v255, s6, 4
	s_add_u32 s3, s26, s0
	s_mul_i32 s2, s5, 0xc00
	v_writelane_b32 v255, s7, 5
	v_writelane_b32 v255, s3, 6
	s_addc_u32 s3, s27, 0
	v_readlane_b32 s36, v250, 29
	v_readlane_b32 s37, v250, 30
	s_add_u32 s2, s36, s2
	v_writelane_b32 v255, s3, 7
	s_addc_u32 s3, s37, 0
	v_writelane_b32 v255, s2, 8
	v_readlane_b32 s38, v250, 31
	v_readlane_b32 s39, v250, 32
	v_writelane_b32 v255, s3, 9
	v_readlane_b32 s2, v251, 46
	s_add_u32 s0, s2, s0
	v_readlane_b32 s40, v250, 33
	v_readlane_b32 s41, v250, 34
	v_readlane_b32 s42, v250, 35
	v_readlane_b32 s43, v250, 36
	v_readlane_b32 s44, v250, 37
	v_readlane_b32 s45, v250, 38
	v_readlane_b32 s46, v250, 39
	v_readlane_b32 s47, v250, 40
	v_readlane_b32 s48, v250, 41
	v_readlane_b32 s49, v250, 42
	v_readlane_b32 s50, v250, 43
	v_readlane_b32 s51, v250, 44
	v_writelane_b32 v255, s0, 10
	v_readlane_b32 s0, v251, 47
	s_addc_u32 s0, s0, 0
	v_readlane_b32 s36, v250, 13
	v_writelane_b32 v255, s0, 11
	s_lshl_b32 s0, s4, 10
	v_readlane_b32 s50, v250, 27
	v_readlane_b32 s51, v250, 28
	s_add_u32 s0, s50, s0
	v_writelane_b32 v254, s0, 62
	s_addc_u32 s0, s51, 0
	v_writelane_b32 v254, s0, 63
	s_lshl_b32 s0, s5, 7
	v_writelane_b32 v255, s0, 12
	s_lshl_b32 s0, s5, 8
	v_writelane_b32 v255, s0, 13
	v_writelane_b32 v255, s5, 14
	s_lshl_b32 s0, s5, 9
	v_writelane_b32 v255, s0, 16
	v_readlane_b32 s0, v250, 0
	v_readlane_b32 s37, v250, 14
	v_readlane_b32 s38, v250, 15
	v_readlane_b32 s39, v250, 16
	v_readlane_b32 s40, v250, 17
	v_readlane_b32 s41, v250, 18
	v_readlane_b32 s42, v250, 19
	v_readlane_b32 s43, v250, 20
	v_readlane_b32 s44, v250, 21
	v_readlane_b32 s45, v250, 22
	v_readlane_b32 s46, v250, 23
	v_readlane_b32 s47, v250, 24
	v_readlane_b32 s48, v250, 25
	v_readlane_b32 s49, v250, 26
	v_readlane_b32 s2, v250, 7
	s_cmpk_lg_u32 s2, 0x200
	s_cbranch_scc1 .Lms_e
	s_cmpk_lt_u32 s0, 0x80
	s_cbranch_scc0 .Lms_e
	s_addk_i32 s0, 0xc00
.Lms_e:
	s_branch .LBB0_923
.LBB0_921:
	s_or_b64 exec, exec, s[2:3]
.LBB0_922:
	v_readlane_b32 s4, v250, 1
	v_readlane_b32 s10, v250, 7
	v_readlane_b32 s0, v255, 17
	s_add_i32 s0, s0, s10
	v_readlane_b32 s5, v250, 2
	v_readlane_b32 s6, v250, 3
	v_readlane_b32 s7, v250, 4
	v_readlane_b32 s8, v250, 5
	v_readlane_b32 s9, v250, 6
	v_readlane_b32 s11, v250, 8
	s_cmpk_lg_u32 s10, 0x200
	s_cbranch_scc1 .Lms_std
	v_readlane_b32 s2, v250, 0
	s_cmpk_lt_u32 s2, 0x80
	s_cbranch_scc0 .Lms_std
	s_sub_i32 s2, s0, 0xe00
	s_cmpk_lt_u32 s2, 0x80
	s_cbranch_scc0 .Lms_a
	s_mov_b32 s0, s2
	s_branch .LBB0_923
.Lms_a:
	s_sub_i32 s2, s0, 0xc00
	s_cmpk_lt_u32 s2, 0x80
	s_cbranch_scc0 .Lms_std
	s_add_i32 s0, s0, 0x200
.Lms_std:
	s_cmpk_gt_i32 s0, 0xe10
	s_cbranch_scc1 .LBB0_1888
